# v34: v26 with ONE barrier per KV tile in attention (V tiles in a 3-deep LDS ring so the next V write needs no barrier after PV)
# speedup vs baseline: 1.0042x; 1.0042x over previous
.LBB0_525:
	s_mul_i32 s7, s7, 0x9800
	s_mul_hi_u32 s8, s6, 0x9800
	s_and_b32 s4, s10, 15
	s_add_i32 s8, s8, s7
	s_mul_i32 s6, s6, 0x9800
	s_add_u32 s6, s50, s6
	s_addc_u32 s7, s51, s8
	s_lshl_b32 s4, s4, 8
	s_add_u32 s48, s6, s4
	s_addc_u32 s49, s7, 0
	s_lshl_b32 s4, s11, 2
	s_bfe_u32 s6, s10, 0x20002
	s_or_b32 s26, s4, s6
	v_mbcnt_lo_u32_b32 v76, -1, 0
	v_mbcnt_hi_u32_b32 v76, -1, v76
	s_mul_i32 s6, s26, 0x210000
	v_add_u32_e32 v54, s39, v76
	v_ashrrev_i32_e32 v16, 4, v54
	s_mul_hi_i32 s4, s26, 0x210000
	s_add_u32 s40, s52, s6
	v_lshlrev_b32_e32 v22, 3, v76
	v_add_u32_e32 v18, 32, v16
	s_addc_u32 s41, s53, s4
	v_and_b32_e32 v0, 0x78, v22
	v_ashrrev_i32_e32 v17, 31, v16
	v_ashrrev_i32_e32 v19, 31, v18
	s_add_u32 s42, s54, s6
	v_lshlrev_b32_e32 v23, 1, v0
	v_lshlrev_b64 v[48:49], 8, v[16:17]
	v_lshlrev_b64 v[8:9], 8, v[18:19]
	s_addc_u32 s43, s55, s4
	v_or_b32_e32 v52, v48, v23
	v_mov_b32_e32 v53, v49
	v_or_b32_e32 v8, v8, v23
	v_lshl_add_u64 v[0:1], s[42:43], 0, v[52:53]
	v_lshl_add_u64 v[4:5], s[42:43], 0, v[8:9]
	v_lshl_add_u64 v[10:11], s[40:41], 0, v[52:53]
	v_lshl_add_u64 v[12:13], s[40:41], 0, v[8:9]
	global_load_dwordx4 v[0:3], v[0:1], off
	s_nop 0
	global_load_dwordx4 v[4:7], v[4:5], off
	s_nop 0
	global_load_dwordx4 v[8:11], v[10:11], off
	s_nop 0
	global_load_dwordx4 v[12:15], v[12:13], off
	v_ashrrev_i32_e32 v55, 1, v54
	s_movk_i32 s4, 0xffe0
	v_bfe_u32 v97, v76, 5, 1
	v_bfi_b32 v17, s4, v55, v76
	v_mov_b64_e32 v[20:21], s[48:49]
	v_mad_i64_i32 v[20:21], s[6:7], v17, s21, v[20:21]
	v_lshlrev_b32_e32 v50, 4, v97
	v_mov_b32_e32 v51, v96
	v_lshl_add_u64 v[20:21], v[20:21], 0, v[50:51]
	global_load_dwordx4 v[118:121], v[20:21], off
	global_load_dwordx4 v[114:117], v[20:21], off offset:32
	global_load_dwordx4 v[126:129], v[20:21], off offset:64
	global_load_dwordx4 v[122:125], v[20:21], off offset:96
	global_load_dwordx4 v[110:113], v[20:21], off offset:128
	global_load_dwordx4 v[106:109], v[20:21], off offset:160
	global_load_dwordx4 v[102:105], v[20:21], off offset:192
	global_load_dwordx4 v[98:101], v[20:21], off offset:224
	v_bfe_u32 v17, v22, 5, 2
	v_and_b32_e32 v22, 0xfffff0, v16
	v_lshlrev_b32_e32 v24, 1, v16
	v_lshrrev_b32_e32 v25, 1, v16
	v_and_b32_e32 v26, 3, v16
	v_and_b32_e32 v19, 0xf0, v54
	v_lshlrev_b32_e32 v16, 8, v16
	v_and_or_b32 v22, v24, 8, v22
	v_bfe_u32 v24, v24, 1, 3
	v_and_b32_e32 v26, 0xfffff0, v18
	v_lshlrev_b32_e32 v27, 1, v18
	v_bitop3_b32 v16, v23, v16, v19 bitop3:0xde
	v_lshlrev_b32_e32 v18, 8, v18
	v_and_b32_e32 v22, 12, v25
	v_and_or_b32 v26, v27, 8, v26
	v_add_u32_e32 v188, 0, v16
	v_bitop3_b32 v16, v18, v23, v19 bitop3:0xf6
	v_or_b32_e32 v18, v22, v17
	v_and_or_b32 v19, v25, 12, 16
	v_and_b32_e32 v25, 48, v23
	v_lshlrev_b32_e32 v24, 6, v24
	v_add_u32_e32 v189, 0, v16
	v_lshlrev_b32_e32 v16, 9, v18
	v_or_b32_e32 v17, v19, v17
	v_or3_b32 v16, v16, v24, v25
	v_lshlrev_b32_e32 v17, 9, v17
	v_and_b32_e32 v180, 31, v76
	v_lshlrev_b32_e32 v51, 4, v76
	v_or3_b32 v17, v17, v24, v25
	v_add_u32_e32 v190, 0, v16
	v_add_u32_e32 v191, 0, v17
	s_waitcnt vmcnt(0)
	s_add_i32 s4, 0, 0x10000
	s_mov_b64 s[6:7], 0x6000
	v_and_b32_e32 v181, 0xffffffe0, v55
	v_and_b32_e32 v77, 63, v76
	s_mov_b32 s8, s5
	s_mov_b32 s9, s5
	s_mov_b32 s10, s5
	s_mov_b32 s11, s5
	s_mov_b32 s12, s5
	s_waitcnt vmcnt(0)
	ds_write_b128 v190, v[0:3]
	s_waitcnt vmcnt(10)
	ds_write_b128 v191, v[4:7]
	s_waitcnt vmcnt(9)
	ds_write_b128 v188, v[8:11] offset:32768
	s_waitcnt vmcnt(8)
	ds_write_b128 v189, v[12:15] offset:32768
	v_lshlrev_b32_e32 v12, 8, v180
	v_and_b32_e32 v13, 0xf0, v51
	v_bitop3_b32 v0, v50, v12, v13 bitop3:0xde
	v_add_u32_e32 v192, 0, v0
	s_waitcnt lgkmcnt(0)
	s_barrier
	ds_read_b128 v[0:3], v192 offset:32768
	ds_read_b128 v[4:7], v192 offset:40960
	s_waitcnt vmcnt(7) lgkmcnt(1)
	v_mfma_f32_32x32x16_bf16 v[16:31], v[0:3], v[118:121], 0
	v_or_b32_e32 v0, 32, v50
	v_bitop3_b32 v0, v0, v12, v13 bitop3:0xde
	v_add_u32_e32 v200, 0, v0
	v_lshl_add_u64 v[8:9], v[52:53], 0, s[6:7]
	v_lshl_add_u64 v[10:11], s[42:43], 0, v[8:9]
	v_lshlrev_b32_e32 v14, 3, v77
	v_and_b32_e32 v15, 0xc0, v51
	s_waitcnt lgkmcnt(0)
	v_mfma_f32_32x32x16_bf16 v[32:47], v[4:7], v[118:121], 0
	ds_read_b128 v[0:3], v200 offset:32768
	ds_read_b128 v[4:7], v200 offset:40960
	s_mov_b32 s6, s5
	s_mov_b32 s7, s5
	s_mov_b32 s13, s5
	s_mov_b32 s14, s5
	s_mov_b32 s15, s5
	s_mov_b32 s16, s5
	s_waitcnt vmcnt(6) lgkmcnt(1)
	v_mfma_f32_32x32x16_bf16 v[16:31], v[0:3], v[114:117], v[16:31]
	v_or_b32_e32 v0, 64, v50
	v_bitop3_b32 v0, v0, v12, v13 bitop3:0xde
	v_add_u32_e32 v199, 0, v0
	s_mov_b32 s17, s5
	s_mov_b32 s18, s5
	s_mov_b32 s19, s5
	s_cmp_lg_u32 0, -1
	s_waitcnt lgkmcnt(0)
	v_mfma_f32_32x32x16_bf16 v[32:47], v[4:7], v[114:117], v[32:47]
	ds_read_b128 v[0:3], v199 offset:32768
	ds_read_b128 v[4:7], v199 offset:40960
	s_cselect_b32 s27, 0, 0
	v_lshlrev_b32_e32 v183, 2, v97
	v_mov_b32_e32 v185, 0
	s_waitcnt vmcnt(5) lgkmcnt(1)
	v_mfma_f32_32x32x16_bf16 v[16:31], v[0:3], v[126:129], v[16:31]
	v_or_b32_e32 v0, 0x60, v50
	v_bitop3_b32 v0, v0, v12, v13 bitop3:0xde
	v_add_u32_e32 v198, 0, v0
	s_waitcnt lgkmcnt(0)
	v_mfma_f32_32x32x16_bf16 v[32:47], v[4:7], v[126:129], v[32:47]
	ds_read_b128 v[0:3], v198 offset:32768
	ds_read_b128 v[4:7], v198 offset:40960
	s_waitcnt vmcnt(4) lgkmcnt(1)
	v_mfma_f32_32x32x16_bf16 v[16:31], v[0:3], v[122:125], v[16:31]
	v_or_b32_e32 v0, 0x80, v50
	v_bitop3_b32 v0, v0, v12, v13 bitop3:0xde
	v_add_u32_e32 v195, 0, v0
	s_waitcnt lgkmcnt(0)
	v_mfma_f32_32x32x16_bf16 v[32:47], v[4:7], v[122:125], v[32:47]
	ds_read_b128 v[0:3], v195 offset:32768
	ds_read_b128 v[4:7], v195 offset:40960
	s_waitcnt vmcnt(3) lgkmcnt(1)
	v_mfma_f32_32x32x16_bf16 v[16:31], v[0:3], v[110:113], v[16:31]
	v_or_b32_e32 v0, 0xa0, v50
	v_bitop3_b32 v0, v0, v12, v13 bitop3:0xde
	v_add_u32_e32 v193, 0, v0
	ds_read_b128 v[0:3], v193 offset:32768
	s_waitcnt lgkmcnt(1)
	v_mfma_f32_32x32x16_bf16 v[32:47], v[4:7], v[110:113], v[32:47]
	v_and_b32_e32 v4, 0x3fffffc0, v54
	v_lshl_add_u32 v78, v4, 2, s4
	ds_read_b128 v[4:7], v193 offset:40960
	s_mov_b32 s4, s5
	v_add_u32_e32 v182, v78, v50
	v_lshl_add_u32 v184, v180, 2, v78
	s_waitcnt vmcnt(2) lgkmcnt(1)
	v_mfma_f32_32x32x16_bf16 v[16:31], v[0:3], v[106:109], v[16:31]
	v_lshl_add_u64 v[0:1], v[52:53], 0, s[68:69]
	v_lshl_add_u64 v[2:3], s[42:43], 0, v[0:1]
	v_lshl_add_u64 v[0:1], s[40:41], 0, v[0:1]
	global_load_dwordx4 v[54:57], v[2:3], off
	global_load_dwordx4 v[58:61], v[10:11], off
	v_lshl_add_u64 v[2:3], s[40:41], 0, v[8:9]
	global_load_dwordx4 v[62:65], v[0:1], off
	global_load_dwordx4 v[66:69], v[2:3], off
	v_or_b32_e32 v0, 0xc0, v50
	v_bitop3_b32 v0, v0, v12, v13 bitop3:0xde
	v_add_u32_e32 v202, 0, v0
	ds_read_b128 v[0:3], v202 offset:32768
	v_lshlrev_b32_e32 v9, 1, v76
	v_and_or_b32 v8, v14, 24, v15
	s_waitcnt lgkmcnt(1)
	v_mfma_f32_32x32x16_bf16 v[32:47], v[4:7], v[106:109], v[32:47]
	v_and_b32_e32 v4, 32, v9
	v_and_b32_e32 v5, 0x100, v14
	v_or3_b32 v51, v8, v4, v5
	ds_read_b128 v[4:7], v202 offset:40960
	v_add_u32_e32 v187, s27, v51
	s_waitcnt vmcnt(5) lgkmcnt(1)
	v_mfma_f32_32x32x16_bf16 v[16:31], v[0:3], v[102:105], v[16:31]
	v_or_b32_e32 v0, 0xe0, v50
	v_bitop3_b32 v0, v0, v12, v13 bitop3:0xde
	v_add_u32_e32 v201, 0, v0
	ds_read_b128 v[0:3], v201 offset:32768
	ds_read_b128 v[70:73], v201 offset:40960
	s_waitcnt lgkmcnt(2)
	v_mfma_f32_32x32x16_bf16 v[32:47], v[4:7], v[102:105], v[32:47]
	s_waitcnt vmcnt(4) lgkmcnt(1)
	v_mfma_f32_32x32x16_bf16 v[16:31], v[0:3], v[98:101], v[16:31]
	v_mov_b64_e32 v[0:1], s[4:5]
	v_mov_b64_e32 v[2:3], s[6:7]
	v_mov_b64_e32 v[4:5], s[8:9]
	v_mov_b64_e32 v[6:7], s[10:11]
	v_mov_b64_e32 v[8:9], s[12:13]
	v_mov_b64_e32 v[10:11], s[14:15]
	v_mov_b64_e32 v[12:13], s[16:17]
	s_waitcnt lgkmcnt(0)
	v_mfma_f32_32x32x16_bf16 v[32:47], v[70:73], v[98:101], v[32:47]
	s_nop 2
	v_max_f32_e32 v70, v17, v17
	v_max_f32_e32 v71, v16, v16
	v_max_f32_e32 v70, v71, v70
	v_max3_f32 v70, v70, v18, v19
	v_max3_f32 v70, v70, v20, v21
	v_max3_f32 v70, v70, v22, v23
	v_max3_f32 v70, v70, v24, v25
	v_max3_f32 v70, v70, v26, v27
	v_max3_f32 v70, v70, v28, v29
	v_max3_f32 v70, v70, v30, v31
	v_max3_f32 v70, v70, v32, v33
	v_max3_f32 v70, v70, v34, v35
	v_max3_f32 v70, v70, v36, v37
	v_max3_f32 v70, v70, v38, v39
	v_max3_f32 v70, v70, v40, v41
	v_max3_f32 v70, v70, v42, v43
	v_mov_b64_e32 v[14:15], s[18:19]
	v_max3_f32 v70, v70, v44, v45
	s_mov_b64 s[6:7], 0x8000
	v_max3_f32 v79, v70, v46, v47
	v_lshl_add_u64 v[70:71], v[52:53], 0, s[6:7]
	s_mov_b64 s[6:7], 0xa000
	v_lshl_add_u64 v[72:73], s[42:43], 0, v[70:71]
	v_lshl_add_u64 v[52:53], v[52:53], 0, s[6:7]
	v_lshl_add_u64 v[70:71], s[40:41], 0, v[70:71]
	v_lshl_add_u64 v[74:75], s[42:43], 0, v[52:53]
	global_load_dwordx4 v[130:133], v[72:73], off
	global_load_dwordx4 v[138:141], v[74:75], off
	v_lshl_add_u64 v[52:53], s[40:41], 0, v[52:53]
	global_load_dwordx4 v[134:137], v[70:71], off
	global_load_dwordx4 v[142:145], v[52:53], off
	v_mov_b32_e32 v80, v79
	s_nop 1
	v_permlane32_swap_b32_e32 v79, v80
	v_max_f32_e32 v52, v80, v80
	v_max_f32_e32 v53, v79, v79
	v_max_f32_e32 v52, v53, v52
	v_add_f32_e32 v53, 0x7149f2ca, v52
	v_max_f32_e32 v52, 0xf149f2ca, v52
	v_cmp_ge_f32_e32 vcc, s92, v53
	v_sub_f32_e32 v53, 0xf149f2ca, v52
	v_mul_f32_e32 v53, 0x3e0293ee, v53
	v_exp_f32_e32 v53, v53
	s_cmp_eq_u64 vcc, exec
	s_cselect_b64 vcc, -1, 0
	s_waitcnt vmcnt(4)
	v_cndmask_b32_e64 v203, v53, 1.0, vcc
	v_mov_b32_e32 v53, 0xf149f2ca
	v_cndmask_b32_e32 v170, v52, v53, vcc
	v_mul_f32_e32 v52, 0xbe0293ee, v170
	v_fmamk_f32 v16, v16, 0x3e0293ee, v52
	v_exp_f32_e32 v163, v16
	v_fmamk_f32 v16, v17, 0x3e0293ee, v52
	v_exp_f32_e32 v177, v16
	v_fmamk_f32 v16, v18, 0x3e0293ee, v52
	v_exp_f32_e32 v164, v16
	v_fmamk_f32 v16, v19, 0x3e0293ee, v52
	v_exp_f32_e32 v207, v16
	v_fmamk_f32 v16, v20, 0x3e0293ee, v52
	v_exp_f32_e32 v176, v16
	v_fmamk_f32 v16, v21, 0x3e0293ee, v52
	v_exp_f32_e32 v210, v16
	v_fmamk_f32 v16, v22, 0x3e0293ee, v52
	v_exp_f32_e32 v165, v16
	v_fmamk_f32 v16, v23, 0x3e0293ee, v52
	v_exp_f32_e32 v175, v16
	v_fmamk_f32 v16, v24, 0x3e0293ee, v52
	v_exp_f32_e32 v166, v16
	v_fmamk_f32 v16, v25, 0x3e0293ee, v52
	v_exp_f32_e32 v173, v16
	v_fmamk_f32 v16, v26, 0x3e0293ee, v52
	v_exp_f32_e32 v167, v16
	v_fmamk_f32 v16, v27, 0x3e0293ee, v52
	v_exp_f32_e32 v174, v16
	v_fmamk_f32 v16, v28, 0x3e0293ee, v52
	v_exp_f32_e32 v168, v16
	v_fmamk_f32 v16, v29, 0x3e0293ee, v52
	v_exp_f32_e32 v171, v16
	v_fmamk_f32 v16, v30, 0x3e0293ee, v52
	v_pk_fma_f32 v[146:147], v[46:47], s[88:89], v[52:53] op_sel_hi:[1,0,0]
	v_pk_fma_f32 v[152:153], v[44:45], s[88:89], v[52:53] op_sel_hi:[1,0,0]
	v_pk_fma_f32 v[156:157], v[42:43], s[88:89], v[52:53] op_sel_hi:[1,0,0]
	v_pk_fma_f32 v[148:149], v[40:41], s[88:89], v[52:53] op_sel_hi:[1,0,0]
	v_pk_fma_f32 v[150:151], v[38:39], s[88:89], v[52:53] op_sel_hi:[1,0,0]
	v_pk_fma_f32 v[154:155], v[36:37], s[88:89], v[52:53] op_sel_hi:[1,0,0]
	v_pk_fma_f32 v[158:159], v[34:35], s[88:89], v[52:53] op_sel_hi:[1,0,0]
	v_pk_fma_f32 v[160:161], v[32:33], s[88:89], v[52:53] op_sel_hi:[1,0,0]
	v_exp_f32_e32 v169, v16
	v_fmac_f32_e32 v52, 0x3e0293ee, v31
	v_mov_b32_e32 v16, 0x210000
	v_exp_f32_e32 v172, v52
	v_mad_i64_i32 v[16:17], s[6:7], s26, v16, v[48:49]
	v_and_b32_e32 v18, 15, v76
	s_addk_i32 s27, 0x4000
	v_lshl_or_b32 v16, v18, 4, v16
	s_waitcnt vmcnt(7)
	ds_write_b128 v190, v[54:57] offset:16384
	s_waitcnt vmcnt(6)
	ds_write_b128 v191, v[58:61] offset:16384
	s_waitcnt vmcnt(5)
	ds_write_b128 v188, v[62:65] offset:49152
	s_waitcnt vmcnt(4)
	ds_write_b128 v189, v[66:69] offset:49152
	v_add_u32_e32 v186, s27, v51
	v_lshl_add_u64 v[178:179], s[46:47], 0, v[16:17]
	v_mov_b64_e32 v[62:63], v[14:15]
	v_mov_b64_e32 v[46:47], v[14:15]
	v_mov_b64_e32 v[30:31], v[14:15]
	v_cmp_gt_u32_e64 s[40:41], 32, v77
	v_mov_b64_e32 v[60:61], v[12:13]
	v_mov_b64_e32 v[58:59], v[10:11]
	v_mov_b64_e32 v[56:57], v[8:9]
	v_mov_b64_e32 v[54:55], v[6:7]
	v_mov_b64_e32 v[52:53], v[4:5]
	v_mov_b64_e32 v[50:51], v[2:3]
	v_mov_b64_e32 v[48:49], v[0:1]
	v_mov_b64_e32 v[44:45], v[12:13]
	v_mov_b64_e32 v[42:43], v[10:11]
	v_mov_b64_e32 v[40:41], v[8:9]
	v_mov_b64_e32 v[38:39], v[6:7]
	v_mov_b64_e32 v[36:37], v[4:5]
	v_mov_b64_e32 v[34:35], v[2:3]
	v_mov_b64_e32 v[32:33], v[0:1]
	v_mov_b64_e32 v[28:29], v[12:13]
	v_mov_b64_e32 v[26:27], v[10:11]
	v_mov_b64_e32 v[24:25], v[8:9]
	v_mov_b64_e32 v[22:23], v[6:7]
	v_mov_b64_e32 v[20:21], v[4:5]
	v_mov_b64_e32 v[18:19], v[2:3]
	v_mov_b64_e32 v[16:17], v[0:1]
	s_waitcnt lgkmcnt(0)
	s_barrier
	v_readfirstlane_b32 s66, v178
	v_readfirstlane_b32 s67, v179
	s_nop 3
	v_subrev_u32_e32 v178, s66, v178
	v_add_u32_e32 v179, 0x2000, v178
	s_add_u32 s98, s66, 0xfef7a000
	s_addc_u32 s99, s67, -1
	s_add_u32 s66, s66, 0xffffa000
	s_addc_u32 s67, s67, -1
	v_mov_b32_e32 v243, v170
	v_mul_f32_e32 v242, 0xbe0293ee, v243
	s_mov_b32 s100, 0
	s_mov_b32 s101, 0x14000
.LBB0_526:
	ds_read_b128 v[64:67], v192 offset:49152
	ds_read_b128 v[68:71], v192 offset:57344
	ds_read_b128 v[232:235], v200 offset:49152
	ds_read_b128 v[236:239], v200 offset:57344
	ds_read_b128 v[250:253], v199 offset:49152
	ds_read_b128 v[244:247], v199 offset:57344
	ds_read_b128 v[212:215], v198 offset:49152
	ds_read_b128 v[216:219], v198 offset:57344
	v_add_u32_e32 v186, s100, v187
	v_add_f32_e32 v162, v163, v177
	s_waitcnt lgkmcnt(6)
	v_mfma_f32_32x32x16_bf16 v[80:95], v[64:67], v[118:121], 0
	v_add_f32_e32 v162, v164, v162
	v_add_f32_e32 v162, v207, v162
	v_add_f32_e32 v162, v176, v162
	v_add_f32_e32 v162, v210, v162
	v_mfma_f32_32x32x16_bf16 v[64:79], v[68:71], v[118:121], 0
	v_add_f32_e32 v162, v165, v162
	v_add_f32_e32 v162, v175, v162
	v_add_f32_e32 v162, v166, v162
	v_add_f32_e32 v162, v173, v162
	v_add_f32_e32 v162, v167, v162
	s_waitcnt lgkmcnt(4)
	v_mfma_f32_32x32x16_bf16 v[80:95], v[232:235], v[114:117], v[80:95]
	ds_read_b128 v[232:235], v195 offset:49152
	v_add_f32_e32 v162, v174, v162
	v_exp_f32_e32 v160, v160
	v_add_f32_e32 v162, v168, v162
	v_exp_f32_e32 v161, v161
	v_mfma_f32_32x32x16_bf16 v[64:79], v[236:239], v[114:117], v[64:79]
	ds_read_b128 v[236:239], v195 offset:57344
	v_add_f32_e32 v162, v171, v162
	v_exp_f32_e32 v158, v158
	v_add_f32_e32 v162, v169, v162
	v_exp_f32_e32 v159, v159
	s_waitcnt lgkmcnt(4)
	v_mfma_f32_32x32x16_bf16 v[80:95], v[250:253], v[126:129], v[80:95]
	ds_read_b128 v[250:253], v193 offset:49152
	v_add_f32_e32 v162, v172, v162
	v_exp_f32_e32 v154, v154
	v_add_f32_e32 v162, v160, v162
	v_exp_f32_e32 v155, v155
	v_mfma_f32_32x32x16_bf16 v[64:79], v[244:247], v[126:129], v[64:79]
	ds_read_b128 v[244:247], v193 offset:57344
	v_add_f32_e32 v162, v161, v162
	v_exp_f32_e32 v150, v150
	v_add_f32_e32 v162, v158, v162
	v_exp_f32_e32 v151, v151
	s_waitcnt lgkmcnt(4)
	v_mfma_f32_32x32x16_bf16 v[80:95], v[212:215], v[122:125], v[80:95]
	ds_read_b128 v[212:215], v202 offset:49152
	v_add_f32_e32 v162, v159, v162
	v_exp_f32_e32 v148, v148
	v_add_f32_e32 v162, v154, v162
	v_exp_f32_e32 v149, v149
	v_mfma_f32_32x32x16_bf16 v[64:79], v[216:219], v[122:125], v[64:79]
	ds_read_b128 v[216:219], v202 offset:57344
	v_add_f32_e32 v162, v155, v162
	v_exp_f32_e32 v156, v156
	v_add_f32_e32 v162, v150, v162
	v_exp_f32_e32 v157, v157
	s_waitcnt lgkmcnt(4)
	v_mfma_f32_32x32x16_bf16 v[80:95], v[232:235], v[110:113], v[80:95]
	ds_read_b128 v[232:235], v201 offset:49152
	v_add_f32_e32 v162, v151, v162
	v_exp_f32_e32 v152, v152
	v_add_f32_e32 v162, v148, v162
	v_exp_f32_e32 v153, v153
	v_mfma_f32_32x32x16_bf16 v[64:79], v[236:239], v[110:113], v[64:79]
	ds_read_b128 v[236:239], v201 offset:57344
	v_add_f32_e32 v162, v149, v162
	v_exp_f32_e32 v146, v146
	v_add_f32_e32 v162, v156, v162
	v_exp_f32_e32 v147, v147
	s_waitcnt lgkmcnt(4)
	v_mfma_f32_32x32x16_bf16 v[80:95], v[250:253], v[106:109], v[80:95]
	v_add_f32_e32 v162, v157, v162
	v_add_f32_e32 v162, v152, v162
	v_add_f32_e32 v162, v153, v162
	v_add_f32_e32 v162, v146, v162
	v_add_f32_e32 v204, v147, v162
	v_mov_b32_e32 v205, v204
	v_mfma_f32_32x32x16_bf16 v[64:79], v[244:247], v[106:109], v[64:79]
	s_nop 0
	v_permlane32_swap_b32_e32 v204, v205
	v_cvt_pk_bf16_f32 v162, v163, v177
	v_cvt_pk_bf16_f32 v163, v164, v207
	v_cvt_pk_bf16_f32 v164, v176, v210
	s_waitcnt lgkmcnt(2)
	v_mfma_f32_32x32x16_bf16 v[80:95], v[212:215], v[102:105], v[80:95]
	v_cvt_pk_bf16_f32 v165, v165, v175
	v_cvt_pk_bf16_f32 v166, v166, v173
	v_cvt_pk_bf16_f32 v167, v167, v174
	v_cvt_pk_bf16_f32 v168, v168, v171
	v_mfma_f32_32x32x16_bf16 v[64:79], v[216:219], v[102:105], v[64:79]
	v_cvt_pk_bf16_f32 v169, v169, v172
	v_cvt_pk_bf16_f32 v172, v160, v161
	v_cvt_pk_bf16_f32 v173, v158, v159
	v_cvt_pk_bf16_f32 v174, v154, v155
	ds_read_b64_tr_b16 v[210:211], v186 offset:0x0
	ds_read_b64_tr_b16 v[212:213], v186 offset:0x800
	ds_read_b64_tr_b16 v[214:215], v186 offset:0x200
	ds_read_b64_tr_b16 v[216:217], v186 offset:0xa00
	ds_read_b64_tr_b16 v[218:219], v186 offset:0x400
	ds_read_b64_tr_b16 v[220:221], v186 offset:0xc00
	ds_read_b64_tr_b16 v[222:223], v186 offset:0x600
	ds_read_b64_tr_b16 v[224:225], v186 offset:0xe00
	s_waitcnt lgkmcnt(8)
	v_mfma_f32_32x32x16_bf16 v[80:95], v[232:235], v[98:101], v[80:95]
	v_cvt_pk_bf16_f32 v175, v150, v151
	v_cvt_pk_bf16_f32 v206, v148, v149
	v_cvt_pk_bf16_f32 v207, v156, v157
	v_mfma_f32_32x32x16_bf16 v[64:79], v[236:239], v[98:101], v[64:79]
	v_cvt_pk_bf16_f32 v208, v152, v153
	v_cvt_pk_bf16_f32 v209, v146, v147
	s_waitcnt vmcnt(0)
	ds_write_b128 v188, v[134:137] offset:32768
	ds_write_b128 v189, v[142:145] offset:32768
	global_load_dwordx4 v[146:149], v178, s[66:67]
	global_load_dwordx4 v[150:153], v179, s[66:67]
	global_load_dwordx4 v[154:157], v178, s[98:99]
	global_load_dwordx4 v[158:161], v179, s[98:99]
	s_add_u32 s66, s66, 0x4000
	s_addc_u32 s67, s67, 0
	s_add_u32 s98, s98, 0x4000
	s_addc_u32 s99, s99, 0
	s_waitcnt lgkmcnt(6)
	v_mfma_f32_32x32x16_bf16 v[0:15], v[162:165], v[210:213], v[0:15]
	ds_read_b64_tr_b16 v[210:211], v186 offset:0x1000
	ds_read_b64_tr_b16 v[212:213], v186 offset:0x1800
	v_max_f32_e32 v240, v80, v81
	v_max3_f32 v240, v240, v82, v83
	v_max3_f32 v240, v240, v84, v85
	v_max3_f32 v240, v240, v86, v87
	v_max3_f32 v240, v240, v88, v89
	v_mfma_f32_32x32x16_bf16 v[48:63], v[162:165], v[214:217], v[48:63]
	ds_read_b64_tr_b16 v[214:215], v186 offset:0x1200
	ds_read_b64_tr_b16 v[216:217], v186 offset:0x1a00
	v_max3_f32 v240, v240, v90, v91
	v_max3_f32 v240, v240, v92, v93
	v_max3_f32 v240, v240, v94, v95
	v_max3_f32 v240, v240, v64, v65
	v_max3_f32 v240, v240, v66, v67
	v_max3_f32 v240, v240, v68, v69
	s_waitcnt lgkmcnt(6)
	v_mfma_f32_32x32x16_bf16 v[32:47], v[162:165], v[218:221], v[32:47]
	ds_read_b64_tr_b16 v[218:219], v186 offset:0x1400
	ds_read_b64_tr_b16 v[220:221], v186 offset:0x1c00
	v_max3_f32 v240, v240, v70, v71
	v_max3_f32 v240, v240, v72, v73
	v_max3_f32 v240, v240, v74, v75
	v_max3_f32 v240, v240, v76, v77
	v_max3_f32 v240, v240, v78, v79
	v_mfma_f32_32x32x16_bf16 v[16:31], v[162:165], v[222:225], v[16:31]
	ds_read_b64_tr_b16 v[222:223], v186 offset:0x1600
	ds_read_b64_tr_b16 v[224:225], v186 offset:0x1e00
	v_mov_b32_e32 v241, v240
	s_nop 1
	v_permlane32_swap_b32_e32 v240, v241
	v_max_f32_e32 v240, v240, v241
	v_sub_f32_e32 v241, v240, v243
	v_cmp_ge_f32_e32 vcc, s92, v241
	s_waitcnt lgkmcnt(4)
	v_mfma_f32_32x32x16_bf16 v[0:15], v[166:169], v[210:213], v[0:15]
	ds_read_b64_tr_b16 v[210:211], v186 offset:0x2000
	ds_read_b64_tr_b16 v[212:213], v186 offset:0x2800
	s_cmp_eq_u64 vcc, exec
	s_cselect_b64 s[42:43], -1, 0
	s_cbranch_scc1 .Lattn_common_a
	v_max_f32_e32 v240, v243, v240
	v_sub_f32_e32 v241, v243, v240
	v_mul_f32_e32 v241, 0x3e0293ee, v241
	v_exp_f32_e32 v241, v241
	v_mov_b32_e32 v243, v240
	v_mul_f32_e32 v242, 0xbe0293ee, v243
.Lattn_common_a:
	v_mfma_f32_32x32x16_bf16 v[48:63], v[166:169], v[214:217], v[48:63]
	ds_read_b64_tr_b16 v[214:215], v186 offset:0x2200
	ds_read_b64_tr_b16 v[216:217], v186 offset:0x2a00
	v_fmamk_f32 v80, v80, 0x3e0293ee, v242
	v_fmamk_f32 v81, v81, 0x3e0293ee, v242
	v_fmamk_f32 v82, v82, 0x3e0293ee, v242
	v_fmamk_f32 v83, v83, 0x3e0293ee, v242
	s_waitcnt lgkmcnt(4)
	v_mfma_f32_32x32x16_bf16 v[32:47], v[166:169], v[218:221], v[32:47]
	ds_read_b64_tr_b16 v[218:219], v186 offset:0x2400
	ds_read_b64_tr_b16 v[220:221], v186 offset:0x2c00
	v_fmamk_f32 v84, v84, 0x3e0293ee, v242
	v_fmamk_f32 v85, v85, 0x3e0293ee, v242
	v_fmamk_f32 v86, v86, 0x3e0293ee, v242
	v_fmamk_f32 v87, v87, 0x3e0293ee, v242
	v_fmamk_f32 v88, v88, 0x3e0293ee, v242
	v_fmamk_f32 v89, v89, 0x3e0293ee, v242
	v_mfma_f32_32x32x16_bf16 v[16:31], v[166:169], v[222:225], v[16:31]
	ds_read_b64_tr_b16 v[222:223], v186 offset:0x2600
	ds_read_b64_tr_b16 v[224:225], v186 offset:0x2e00
	v_fmamk_f32 v90, v90, 0x3e0293ee, v242
	v_fmamk_f32 v91, v91, 0x3e0293ee, v242
	v_fmamk_f32 v92, v92, 0x3e0293ee, v242
	v_fmamk_f32 v93, v93, 0x3e0293ee, v242
	v_fmamk_f32 v94, v94, 0x3e0293ee, v242
	v_fmamk_f32 v95, v95, 0x3e0293ee, v242
	s_waitcnt lgkmcnt(4)
	v_mfma_f32_32x32x16_bf16 v[0:15], v[172:175], v[210:213], v[0:15]
	ds_read_b64_tr_b16 v[210:211], v186 offset:0x3000
	ds_read_b64_tr_b16 v[212:213], v186 offset:0x3800
	v_exp_f32_e32 v177, v81
	v_exp_f32_e32 v176, v83
	v_exp_f32_e32 v171, v93
	v_mfma_f32_32x32x16_bf16 v[48:63], v[172:175], v[214:217], v[48:63]
	ds_read_b64_tr_b16 v[214:215], v186 offset:0x3200
	ds_read_b64_tr_b16 v[216:217], v186 offset:0x3a00
	v_exp_f32_e32 v170, v95
	v_exp_f32_e32 v162, v80
	v_exp_f32_e32 v163, v82
	s_waitcnt lgkmcnt(4)
	v_mfma_f32_32x32x16_bf16 v[32:47], v[172:175], v[218:221], v[32:47]
	ds_read_b64_tr_b16 v[218:219], v186 offset:0x3400
	ds_read_b64_tr_b16 v[220:221], v186 offset:0x3c00
	v_exp_f32_e32 v164, v84
	v_exp_f32_e32 v165, v86
	v_exp_f32_e32 v166, v88
	v_mfma_f32_32x32x16_bf16 v[16:31], v[172:175], v[222:225], v[16:31]
	ds_read_b64_tr_b16 v[222:223], v186 offset:0x3600
	ds_read_b64_tr_b16 v[224:225], v186 offset:0x3e00
	v_exp_f32_e32 v167, v90
	v_exp_f32_e32 v168, v92
	v_exp_f32_e32 v169, v94
	s_waitcnt lgkmcnt(4)
	v_mfma_f32_32x32x16_bf16 v[0:15], v[206:209], v[210:213], v[0:15]
	v_exp_f32_e32 v175, v85
	v_exp_f32_e32 v174, v87
	v_exp_f32_e32 v173, v89
	v_mfma_f32_32x32x16_bf16 v[48:63], v[206:209], v[214:217], v[48:63]
	v_exp_f32_e32 v172, v91
	s_waitcnt lgkmcnt(0)
	v_mfma_f32_32x32x16_bf16 v[32:47], v[206:209], v[218:221], v[32:47]
	v_mfma_f32_32x32x16_bf16 v[16:31], v[206:209], v[222:225], v[16:31]
	v_cndmask_b32_e64 v206, v241, 1.0, s[42:43]
	v_add_u32_e32 v248, s101, v190
	v_add_u32_e32 v249, s101, v191
	ds_write_b128 v248, v[130:133]
	ds_write_b128 v249, v[138:141]
	s_cmp_lg_u64 s[42:43], 0
	s_cbranch_scc1 .LBB0_530
	s_and_saveexec_b64 s[6:7], s[40:41]
	ds_write_b32 v184, v206 offset:128
	s_or_b64 exec, exec, s[6:7]
	s_waitcnt lgkmcnt(0)
	ds_read_b128 v[210:213], v182 offset:224
	ds_read_b128 v[214:217], v182 offset:192
	ds_read_b128 v[218:221], v182 offset:160
	ds_read_b128 v[222:225], v182 offset:128
	s_waitcnt lgkmcnt(3)
	v_pk_mul_f32 v[14:15], v[14:15], v[212:213]
	s_waitcnt lgkmcnt(2)
	v_pk_mul_f32 v[10:11], v[10:11], v[216:217]
	s_waitcnt lgkmcnt(1)
	v_pk_mul_f32 v[6:7], v[6:7], v[220:221]
	s_waitcnt lgkmcnt(0)
	v_pk_mul_f32 v[2:3], v[2:3], v[224:225]
	v_pk_mul_f32 v[12:13], v[12:13], v[210:211]
	v_pk_mul_f32 v[8:9], v[8:9], v[214:215]
	v_pk_mul_f32 v[4:5], v[4:5], v[218:219]
	v_pk_mul_f32 v[0:1], v[0:1], v[222:223]
	v_pk_mul_f32 v[62:63], v[62:63], v[212:213]
	v_pk_mul_f32 v[58:59], v[58:59], v[216:217]
	v_pk_mul_f32 v[54:55], v[54:55], v[220:221]
	v_pk_mul_f32 v[50:51], v[50:51], v[224:225]
	v_pk_mul_f32 v[60:61], v[60:61], v[210:211]
	v_pk_mul_f32 v[56:57], v[56:57], v[214:215]
	v_pk_mul_f32 v[52:53], v[52:53], v[218:219]
	v_pk_mul_f32 v[48:49], v[48:49], v[222:223]
	v_pk_mul_f32 v[46:47], v[46:47], v[212:213]
	v_pk_mul_f32 v[42:43], v[42:43], v[216:217]
	v_pk_mul_f32 v[38:39], v[38:39], v[220:221]
	v_pk_mul_f32 v[34:35], v[34:35], v[224:225]
	v_pk_mul_f32 v[44:45], v[44:45], v[210:211]
	v_pk_mul_f32 v[40:41], v[40:41], v[214:215]
	v_pk_mul_f32 v[36:37], v[36:37], v[218:219]
	v_pk_mul_f32 v[32:33], v[32:33], v[222:223]
	v_pk_mul_f32 v[30:31], v[30:31], v[212:213]
	v_pk_mul_f32 v[26:27], v[26:27], v[216:217]
	v_pk_mul_f32 v[22:23], v[22:23], v[220:221]
	v_pk_mul_f32 v[18:19], v[18:19], v[224:225]
	v_pk_mul_f32 v[28:29], v[28:29], v[210:211]
	v_pk_mul_f32 v[24:25], v[24:25], v[214:215]
	v_pk_mul_f32 v[20:21], v[20:21], v[218:219]
	v_pk_mul_f32 v[16:17], v[16:17], v[222:223]
.LBB0_530:
	v_fmamk_f32 v217, v64, 0x3e0293ee, v242
	v_fmamk_f32 v218, v65, 0x3e0293ee, v242
	v_fmamk_f32 v219, v66, 0x3e0293ee, v242
	v_fmamk_f32 v220, v67, 0x3e0293ee, v242
	v_fmamk_f32 v221, v68, 0x3e0293ee, v242
	v_fmamk_f32 v210, v69, 0x3e0293ee, v242
	v_fmamk_f32 v211, v70, 0x3e0293ee, v242
	v_fmamk_f32 v212, v71, 0x3e0293ee, v242
	v_fmamk_f32 v213, v72, 0x3e0293ee, v242
	v_fmamk_f32 v214, v73, 0x3e0293ee, v242
	v_fmamk_f32 v215, v74, 0x3e0293ee, v242
	v_fmamk_f32 v216, v75, 0x3e0293ee, v242
	v_fmamk_f32 v209, v76, 0x3e0293ee, v242
	v_fmamk_f32 v222, v77, 0x3e0293ee, v242
	v_fmamk_f32 v223, v78, 0x3e0293ee, v242
	v_fmamk_f32 v208, v79, 0x3e0293ee, v242
	s_add_i32 s101, s101, s100
	s_sub_i32 s101, 0x18000, s101
	s_waitcnt lgkmcnt(0)
	s_barrier
	ds_read_b128 v[64:67], v192 offset:32768
	ds_read_b128 v[68:71], v192 offset:40960
	ds_read_b128 v[232:235], v200 offset:32768
	ds_read_b128 v[236:239], v200 offset:40960
	ds_read_b128 v[250:253], v199 offset:32768
	ds_read_b128 v[244:247], v199 offset:40960
	ds_read_b128 v[224:227], v198 offset:32768
	ds_read_b128 v[228:231], v198 offset:40960
	v_add_u32_e32 v186, s101, v187
	v_exp_f32_e32 v248, v208
	v_exp_f32_e32 v249, v209
	s_waitcnt lgkmcnt(6)
	v_mfma_f32_32x32x16_bf16 v[80:95], v[64:67], v[118:121], 0
	v_exp_f32_e32 v217, v217
	v_add_f32_e32 v208, v162, v177
	v_exp_f32_e32 v218, v218
	v_mfma_f32_32x32x16_bf16 v[64:79], v[68:71], v[118:121], 0
	v_add_f32_e32 v208, v163, v208
	v_exp_f32_e32 v219, v219
	v_add_f32_e32 v208, v176, v208
	v_exp_f32_e32 v220, v220
	v_add_f32_e32 v208, v164, v208
	s_waitcnt lgkmcnt(4)
	v_mfma_f32_32x32x16_bf16 v[80:95], v[232:235], v[114:117], v[80:95]
	ds_read_b128 v[232:235], v195 offset:32768
	v_exp_f32_e32 v221, v221
	v_add_f32_e32 v208, v175, v208
	v_exp_f32_e32 v210, v210
	v_add_f32_e32 v208, v165, v208
	v_mfma_f32_32x32x16_bf16 v[64:79], v[236:239], v[114:117], v[64:79]
	ds_read_b128 v[236:239], v195 offset:40960
	v_exp_f32_e32 v211, v211
	v_add_f32_e32 v208, v174, v208
	v_exp_f32_e32 v212, v212
	v_add_f32_e32 v208, v166, v208
	s_waitcnt lgkmcnt(4)
	v_mfma_f32_32x32x16_bf16 v[80:95], v[250:253], v[126:129], v[80:95]
	ds_read_b128 v[250:253], v193 offset:32768
	v_exp_f32_e32 v213, v213
	v_add_f32_e32 v208, v173, v208
	v_exp_f32_e32 v214, v214
	v_add_f32_e32 v208, v167, v208
	v_mfma_f32_32x32x16_bf16 v[64:79], v[244:247], v[126:129], v[64:79]
	ds_read_b128 v[244:247], v193 offset:40960
	v_exp_f32_e32 v215, v215
	v_add_f32_e32 v208, v172, v208
	v_exp_f32_e32 v216, v216
	v_add_f32_e32 v208, v168, v208
	s_waitcnt lgkmcnt(4)
	v_mfma_f32_32x32x16_bf16 v[80:95], v[224:227], v[122:125], v[80:95]
	ds_read_b128 v[224:227], v202 offset:32768
	v_exp_f32_e32 v222, v222
	v_add_f32_e32 v208, v171, v208
	v_exp_f32_e32 v223, v223
	v_add_f32_e32 v208, v169, v208
	v_mfma_f32_32x32x16_bf16 v[64:79], v[228:231], v[122:125], v[64:79]
	ds_read_b128 v[228:231], v202 offset:40960
	v_add_f32_e32 v208, v170, v208
	v_add_f32_e32 v208, v217, v208
	v_add_f32_e32 v208, v218, v208
	v_add_f32_e32 v208, v219, v208
	s_waitcnt lgkmcnt(4)
	v_mfma_f32_32x32x16_bf16 v[80:95], v[232:235], v[110:113], v[80:95]
	ds_read_b128 v[232:235], v201 offset:32768
	v_add_f32_e32 v208, v220, v208
	v_add_f32_e32 v208, v221, v208
	v_add_f32_e32 v208, v210, v208
	v_add_f32_e32 v208, v211, v208
	v_mfma_f32_32x32x16_bf16 v[64:79], v[236:239], v[110:113], v[64:79]
	ds_read_b128 v[236:239], v201 offset:40960
	v_add_f32_e32 v208, v212, v208
	v_add_f32_e32 v208, v213, v208
	v_add_f32_e32 v208, v214, v208
	v_add_f32_e32 v208, v215, v208
	s_waitcnt lgkmcnt(4)
	v_mfma_f32_32x32x16_bf16 v[80:95], v[250:253], v[106:109], v[80:95]
	v_add_f32_e32 v208, v216, v208
	v_add_f32_e32 v208, v249, v208
	v_add_f32_e32 v208, v222, v208
	v_add_f32_e32 v208, v223, v208
	v_mfma_f32_32x32x16_bf16 v[64:79], v[244:247], v[106:109], v[64:79]
	v_add_f32_e32 v208, v248, v208
	v_mov_b32_e32 v209, v208
	v_cvt_pk_bf16_f32 v162, v162, v177
	v_cvt_pk_bf16_f32 v163, v163, v176
	s_waitcnt lgkmcnt(2)
	v_mfma_f32_32x32x16_bf16 v[80:95], v[224:227], v[102:105], v[80:95]
	v_cvt_pk_bf16_f32 v164, v164, v175
	v_cvt_pk_bf16_f32 v165, v165, v174
	v_cvt_pk_bf16_f32 v166, v166, v173
	v_cvt_pk_bf16_f32 v167, v167, v172
	v_mfma_f32_32x32x16_bf16 v[64:79], v[228:231], v[102:105], v[64:79]
	v_cvt_pk_bf16_f32 v168, v168, v171
	v_cvt_pk_bf16_f32 v169, v169, v170
	v_cvt_pk_bf16_f32 v170, v217, v218
	v_cvt_pk_bf16_f32 v171, v219, v220
	s_waitcnt lgkmcnt(0)
	v_mfma_f32_32x32x16_bf16 v[80:95], v[232:235], v[98:101], v[80:95]
	v_cvt_pk_bf16_f32 v172, v221, v210
	v_cvt_pk_bf16_f32 v173, v211, v212
	v_cvt_pk_bf16_f32 v174, v213, v214
	v_cvt_pk_bf16_f32 v175, v215, v216
	v_mfma_f32_32x32x16_bf16 v[64:79], v[236:239], v[98:101], v[64:79]
	v_cvt_pk_bf16_f32 v176, v249, v222
	v_cvt_pk_bf16_f32 v177, v223, v248
	ds_read_b64_tr_b16 v[210:211], v186 offset:0x0
	ds_read_b64_tr_b16 v[212:213], v186 offset:0x800
	ds_read_b64_tr_b16 v[214:215], v186 offset:0x200
	ds_read_b64_tr_b16 v[216:217], v186 offset:0xa00
	ds_read_b64_tr_b16 v[218:219], v186 offset:0x400
	ds_read_b64_tr_b16 v[220:221], v186 offset:0xc00
	ds_read_b64_tr_b16 v[222:223], v186 offset:0x600
	ds_read_b64_tr_b16 v[224:225], v186 offset:0xe00
	s_nop 1
	v_permlane32_swap_b32_e32 v208, v209
	s_waitcnt vmcnt(1)
	ds_write_b128 v188, v[154:157] offset:49152
	s_waitcnt vmcnt(0)
	ds_write_b128 v189, v[158:161] offset:49152
	s_cmp_ge_u32 s34, s35
	s_cselect_b64 s[6:7], -1, 0
	s_cbranch_scc1 .LBB0_532
	global_load_dwordx4 v[130:133], v178, s[66:67]
	global_load_dwordx4 v[134:137], v178, s[98:99]
	global_load_dwordx4 v[138:141], v179, s[66:67]
	global_load_dwordx4 v[142:145], v179, s[98:99]
	s_add_u32 s66, s66, 0x4000
	s_addc_u32 s67, s67, 0
	s_add_u32 s98, s98, 0x4000
	s_addc_u32 s99, s99, 0

.Lattn_common_b:
	v_mfma_f32_32x32x16_bf16 v[48:63], v[166:169], v[214:217], v[48:63]
	ds_read_b64_tr_b16 v[214:215], v186 offset:0x2200
	ds_read_b64_tr_b16 v[216:217], v186 offset:0x2a00
	v_fmamk_f32 v80, v80, 0x3e0293ee, v242
	v_fmamk_f32 v81, v81, 0x3e0293ee, v242
	v_fmamk_f32 v82, v82, 0x3e0293ee, v242
	v_fmamk_f32 v83, v83, 0x3e0293ee, v242
	s_waitcnt lgkmcnt(4)
	v_mfma_f32_32x32x16_bf16 v[32:47], v[166:169], v[218:221], v[32:47]
	ds_read_b64_tr_b16 v[218:219], v186 offset:0x2400
	ds_read_b64_tr_b16 v[220:221], v186 offset:0x2c00
	v_fmamk_f32 v84, v84, 0x3e0293ee, v242
	v_fmamk_f32 v85, v85, 0x3e0293ee, v242
	v_fmamk_f32 v86, v86, 0x3e0293ee, v242
	v_fmamk_f32 v87, v87, 0x3e0293ee, v242
	v_fmamk_f32 v88, v88, 0x3e0293ee, v242
	v_fmamk_f32 v89, v89, 0x3e0293ee, v242
	v_mfma_f32_32x32x16_bf16 v[16:31], v[166:169], v[222:225], v[16:31]
	ds_read_b64_tr_b16 v[222:223], v186 offset:0x2600
	ds_read_b64_tr_b16 v[224:225], v186 offset:0x2e00
	v_fmamk_f32 v90, v90, 0x3e0293ee, v242
	v_fmamk_f32 v91, v91, 0x3e0293ee, v242
	v_fmamk_f32 v92, v92, 0x3e0293ee, v242
	v_fmamk_f32 v93, v93, 0x3e0293ee, v242
	v_fmamk_f32 v94, v94, 0x3e0293ee, v242
	v_fmamk_f32 v95, v95, 0x3e0293ee, v242
	s_waitcnt lgkmcnt(4)
	v_mfma_f32_32x32x16_bf16 v[0:15], v[170:173], v[210:213], v[0:15]
	ds_read_b64_tr_b16 v[210:211], v186 offset:0x3000
	ds_read_b64_tr_b16 v[212:213], v186 offset:0x3800
	v_exp_f32_e32 v207, v83
	v_exp_f32_e32 v163, v80
	v_exp_f32_e32 v164, v82
	v_mfma_f32_32x32x16_bf16 v[48:63], v[170:173], v[214:217], v[48:63]
	ds_read_b64_tr_b16 v[214:215], v186 offset:0x3200
	ds_read_b64_tr_b16 v[216:217], v186 offset:0x3a00
	v_exp_f32_e32 v165, v86
	v_exp_f32_e32 v166, v88
	v_exp_f32_e32 v167, v90
	s_waitcnt lgkmcnt(4)
	v_mfma_f32_32x32x16_bf16 v[32:47], v[170:173], v[218:221], v[32:47]
	ds_read_b64_tr_b16 v[218:219], v186 offset:0x3400
	ds_read_b64_tr_b16 v[220:221], v186 offset:0x3c00
	v_exp_f32_e32 v168, v92
	v_exp_f32_e32 v169, v94
	v_mfma_f32_32x32x16_bf16 v[16:31], v[170:173], v[222:225], v[16:31]
	ds_read_b64_tr_b16 v[222:223], v186 offset:0x3600
	ds_read_b64_tr_b16 v[224:225], v186 offset:0x3e00
	s_waitcnt lgkmcnt(4)
	v_mfma_f32_32x32x16_bf16 v[0:15], v[174:177], v[210:213], v[0:15]
	v_exp_f32_e32 v171, v93
	v_exp_f32_e32 v172, v95
	v_exp_f32_e32 v173, v89
	v_mfma_f32_32x32x16_bf16 v[48:63], v[174:177], v[214:217], v[48:63]
	v_exp_f32_e32 v210, v85
	s_waitcnt lgkmcnt(0)
	v_mfma_f32_32x32x16_bf16 v[32:47], v[174:177], v[218:221], v[32:47]
	v_mfma_f32_32x32x16_bf16 v[16:31], v[174:177], v[222:225], v[16:31]
	v_exp_f32_e32 v174, v91
	v_exp_f32_e32 v175, v87
	v_exp_f32_e32 v176, v84
	v_exp_f32_e32 v177, v81
	v_cndmask_b32_e64 v162, v241, 1.0, s[42:43]
	v_add_u32_e32 v248, s100, v190
	v_add_u32_e32 v249, s100, v191
	ds_write_b128 v248, v[146:149]
	ds_write_b128 v249, v[150:153]
	s_cmp_lg_u64 s[42:43], 0
	s_cbranch_scc1 .LBB0_536
	s_and_saveexec_b64 s[8:9], s[40:41]
	ds_write_b32 v184, v162 offset:128
	s_or_b64 exec, exec, s[8:9]
	s_waitcnt lgkmcnt(0)
	ds_read_b128 v[146:149], v182 offset:224
	ds_read_b128 v[150:153], v182 offset:192
	ds_read_b128 v[154:157], v182 offset:160
	ds_read_b128 v[158:161], v182 offset:128
	s_waitcnt lgkmcnt(3)
	v_pk_mul_f32 v[14:15], v[14:15], v[148:149]
	s_waitcnt lgkmcnt(2)
	v_pk_mul_f32 v[10:11], v[10:11], v[152:153]
	s_waitcnt lgkmcnt(1)
	v_pk_mul_f32 v[6:7], v[6:7], v[156:157]
	s_waitcnt lgkmcnt(0)
	v_pk_mul_f32 v[2:3], v[2:3], v[160:161]
	v_pk_mul_f32 v[12:13], v[12:13], v[146:147]
	v_pk_mul_f32 v[8:9], v[8:9], v[150:151]
	v_pk_mul_f32 v[4:5], v[4:5], v[154:155]
	v_pk_mul_f32 v[0:1], v[0:1], v[158:159]
	v_pk_mul_f32 v[62:63], v[62:63], v[148:149]
	v_pk_mul_f32 v[58:59], v[58:59], v[152:153]
	v_pk_mul_f32 v[54:55], v[54:55], v[156:157]
	v_pk_mul_f32 v[50:51], v[50:51], v[160:161]
	v_pk_mul_f32 v[60:61], v[60:61], v[146:147]
	v_pk_mul_f32 v[56:57], v[56:57], v[150:151]
	v_pk_mul_f32 v[52:53], v[52:53], v[154:155]
	v_pk_mul_f32 v[48:49], v[48:49], v[158:159]
	v_pk_mul_f32 v[46:47], v[46:47], v[148:149]
	v_pk_mul_f32 v[42:43], v[42:43], v[152:153]
	v_pk_mul_f32 v[38:39], v[38:39], v[156:157]
	v_pk_mul_f32 v[34:35], v[34:35], v[160:161]
	v_pk_mul_f32 v[44:45], v[44:45], v[146:147]
	v_pk_mul_f32 v[40:41], v[40:41], v[150:151]
	v_pk_mul_f32 v[36:37], v[36:37], v[154:155]
	v_pk_mul_f32 v[32:33], v[32:33], v[158:159]
	v_pk_mul_f32 v[30:31], v[30:31], v[148:149]
	v_pk_mul_f32 v[26:27], v[26:27], v[152:153]
	v_pk_mul_f32 v[22:23], v[22:23], v[156:157]
	v_pk_mul_f32 v[18:19], v[18:19], v[160:161]
	v_pk_mul_f32 v[28:29], v[28:29], v[146:147]
	v_pk_mul_f32 v[24:25], v[24:25], v[150:151]
	v_pk_mul_f32 v[20:21], v[20:21], v[154:155]
	v_pk_mul_f32 v[16:17], v[16:17], v[158:159]
.LBB0_536:
	s_add_i32 s100, s100, s101
	s_sub_i32 s100, 0x18000, s100
	v_pk_fma_f32 v[160:161], v[64:65], s[88:89], v[242:243] op_sel_hi:[1,0,0]
	v_add_f32_e32 v64, v204, v205
	v_fmac_f32_e32 v64, v203, v185
	v_add_f32_e32 v185, v208, v209
	v_pk_fma_f32 v[158:159], v[66:67], s[88:89], v[242:243] op_sel_hi:[1,0,0]
	v_pk_fma_f32 v[154:155], v[68:69], s[88:89], v[242:243] op_sel_hi:[1,0,0]
	v_pk_fma_f32 v[150:151], v[70:71], s[88:89], v[242:243] op_sel_hi:[1,0,0]
	v_pk_fma_f32 v[148:149], v[72:73], s[88:89], v[242:243] op_sel_hi:[1,0,0]
	v_pk_fma_f32 v[156:157], v[74:75], s[88:89], v[242:243] op_sel_hi:[1,0,0]
	v_pk_fma_f32 v[152:153], v[76:77], s[88:89], v[242:243] op_sel_hi:[1,0,0]
	v_pk_fma_f32 v[146:147], v[78:79], s[88:89], v[242:243] op_sel_hi:[1,0,0]
	v_fmac_f32_e32 v185, v64, v206
	s_add_i32 s34, s34, 2
	s_and_b64 vcc, exec, s[6:7]
	s_waitcnt lgkmcnt(0)
	s_barrier
	s_cbranch_vccnz .LBB0_538
	v_mov_b32_e32 v203, v162
	s_branch .LBB0_526
.LBB0_538:
	v_mov_b32_e32 v170, v243
	s_add_i32 vcc_lo, s100, s101
	s_sub_i32 vcc_lo, 0x18000, vcc_lo
	v_add_u32_e32 v186, vcc_lo, v187
	v_add_u32_e32 v187, s100, v187
	ds_read_b128 v[64:67], v192 offset:49152
	ds_read_b128 v[68:71], v192 offset:57344
	s_waitcnt lgkmcnt(1)
	v_mfma_f32_32x32x16_bf16 v[80:95], v[64:67], v[118:121], 0
	s_waitcnt lgkmcnt(0)
	v_mfma_f32_32x32x16_bf16 v[64:79], v[68:71], v[118:121], 0
	ds_read_b128 v[118:121], v200 offset:49152
	ds_read_b128 v[130:133], v200 offset:57344
	s_waitcnt lgkmcnt(1)
	v_mfma_f32_32x32x16_bf16 v[80:95], v[118:121], v[114:117], v[80:95]
	s_waitcnt lgkmcnt(0)
	v_mfma_f32_32x32x16_bf16 v[64:79], v[130:133], v[114:117], v[64:79]
	ds_read_b128 v[114:117], v199 offset:49152
	ds_read_b128 v[118:121], v199 offset:57344
	s_waitcnt lgkmcnt(1)
	v_mfma_f32_32x32x16_bf16 v[80:95], v[114:117], v[126:129], v[80:95]
	s_waitcnt lgkmcnt(0)
	v_mfma_f32_32x32x16_bf16 v[64:79], v[118:121], v[126:129], v[64:79]
	ds_read_b128 v[114:117], v198 offset:49152
	ds_read_b128 v[118:121], v198 offset:57344
	s_waitcnt lgkmcnt(1)
	v_mfma_f32_32x32x16_bf16 v[80:95], v[114:117], v[122:125], v[80:95]
	s_waitcnt lgkmcnt(0)
	v_mfma_f32_32x32x16_bf16 v[64:79], v[118:121], v[122:125], v[64:79]
	ds_read_b128 v[114:117], v195 offset:49152
	ds_read_b128 v[118:121], v195 offset:57344
	v_exp_f32_e32 v122, v146
	v_exp_f32_e32 v123, v147
	s_waitcnt lgkmcnt(1)
	v_mfma_f32_32x32x16_bf16 v[80:95], v[114:117], v[110:113], v[80:95]
	s_waitcnt lgkmcnt(0)
	v_mfma_f32_32x32x16_bf16 v[64:79], v[118:121], v[110:113], v[64:79]
	ds_read_b128 v[110:113], v193 offset:49152
	ds_read_b128 v[114:117], v193 offset:57344
	v_exp_f32_e32 v118, v156
	v_exp_f32_e32 v119, v157
	v_exp_f32_e32 v120, v152
	v_exp_f32_e32 v121, v153
	s_waitcnt lgkmcnt(1)
	v_mfma_f32_32x32x16_bf16 v[80:95], v[110:113], v[106:109], v[80:95]
	s_waitcnt lgkmcnt(0)
	v_mfma_f32_32x32x16_bf16 v[64:79], v[114:117], v[106:109], v[64:79]
	ds_read_b128 v[106:109], v202 offset:49152
	ds_read_b128 v[110:113], v202 offset:57344
	v_exp_f32_e32 v114, v150
	v_exp_f32_e32 v115, v151
	v_exp_f32_e32 v116, v148
	v_exp_f32_e32 v117, v149
	s_waitcnt lgkmcnt(1)
	v_mfma_f32_32x32x16_bf16 v[80:95], v[106:109], v[102:105], v[80:95]
	s_waitcnt lgkmcnt(0)
	v_mfma_f32_32x32x16_bf16 v[64:79], v[110:113], v[102:105], v[64:79]
	ds_read_b128 v[102:105], v201 offset:49152
	ds_read_b128 v[106:109], v201 offset:57344
	v_exp_f32_e32 v110, v158
	v_exp_f32_e32 v111, v159
	v_exp_f32_e32 v112, v154
	v_exp_f32_e32 v113, v155
	s_waitcnt lgkmcnt(1)
	v_mfma_f32_32x32x16_bf16 v[80:95], v[102:105], v[98:101], v[80:95]
	s_waitcnt lgkmcnt(0)
	v_mfma_f32_32x32x16_bf16 v[64:79], v[106:109], v[98:101], v[64:79]
	v_add_f32_e32 v98, 0, v163
	v_add_f32_e32 v98, v177, v98
	v_add_f32_e32 v98, v164, v98
	v_add_f32_e32 v98, v207, v98
	v_add_f32_e32 v98, v176, v98
	v_add_f32_e32 v98, v210, v98
	v_add_f32_e32 v98, v165, v98
	v_add_f32_e32 v98, v175, v98
	v_add_f32_e32 v98, v166, v98
	v_add_f32_e32 v98, v173, v98
	v_add_f32_e32 v98, v167, v98
	v_add_f32_e32 v98, v174, v98
	v_exp_f32_e32 v108, v160
	v_add_f32_e32 v98, v168, v98
	v_exp_f32_e32 v109, v161
	v_add_f32_e32 v98, v171, v98
	v_add_f32_e32 v98, v169, v98
	v_add_f32_e32 v98, v172, v98
	v_add_f32_e32 v98, v108, v98
	v_add_f32_e32 v98, v109, v98
	v_add_f32_e32 v98, v110, v98
	v_add_f32_e32 v98, v111, v98
	v_add_f32_e32 v98, v112, v98
	v_add_f32_e32 v98, v113, v98
	v_add_f32_e32 v98, v114, v98
	v_add_f32_e32 v98, v115, v98
	v_add_f32_e32 v98, v116, v98
	v_add_f32_e32 v98, v117, v98
	v_add_f32_e32 v98, v118, v98
	v_add_f32_e32 v98, v119, v98
	v_add_f32_e32 v98, v120, v98
	v_add_f32_e32 v98, v121, v98
	v_add_f32_e32 v98, v122, v98
	v_add_f32_e32 v98, v123, v98
	v_mov_b32_e32 v99, v98
	v_cvt_pk_bf16_f32 v100, v163, v177
	v_cvt_pk_bf16_f32 v101, v164, v207
	v_cvt_pk_bf16_f32 v102, v176, v210
	v_cvt_pk_bf16_f32 v103, v165, v175
	s_nop 1
	v_permlane32_swap_b32_e32 v98, v99
	v_cvt_pk_bf16_f32 v104, v166, v173
	v_cvt_pk_bf16_f32 v105, v167, v174
	v_cvt_pk_bf16_f32 v106, v168, v171
	v_cvt_pk_bf16_f32 v107, v169, v172
	v_cvt_pk_bf16_f32 v108, v108, v109
	v_cvt_pk_bf16_f32 v109, v110, v111
	v_cvt_pk_bf16_f32 v110, v112, v113
	v_cvt_pk_bf16_f32 v111, v114, v115
	v_cvt_pk_bf16_f32 v112, v116, v117
	v_cvt_pk_bf16_f32 v113, v118, v119
	v_cvt_pk_bf16_f32 v114, v120, v121
	v_cvt_pk_bf16_f32 v115, v122, v123
	s_nop 0
	ds_read_b64_tr_b16 v[116:117], v187 offset:0
	ds_read_b64_tr_b16 v[118:119], v187 offset:0x800
	ds_read_b64_tr_b16 v[120:121], v187 offset:0x1000
	ds_read_b64_tr_b16 v[122:123], v187 offset:0x1800
	ds_read_b64_tr_b16 v[124:125], v187 offset:0x2000
	ds_read_b64_tr_b16 v[126:127], v187 offset:0x2800
	ds_read_b64_tr_b16 v[128:129], v187 offset:0x3000
	ds_read_b64_tr_b16 v[130:131], v187 offset:0x3800
	s_waitcnt lgkmcnt(0)
	s_nop 0
	v_mfma_f32_32x32x16_bf16 v[0:15], v[100:103], v[116:119], v[0:15]
	ds_read_b64_tr_b16 v[116:117], v187 offset:0x200
	ds_read_b64_tr_b16 v[118:119], v187 offset:0xa00
	v_mfma_f32_32x32x16_bf16 v[0:15], v[104:107], v[120:123], v[0:15]
	ds_read_b64_tr_b16 v[120:121], v187 offset:0x1200
	ds_read_b64_tr_b16 v[122:123], v187 offset:0x1a00
	v_mfma_f32_32x32x16_bf16 v[0:15], v[108:111], v[124:127], v[0:15]
	ds_read_b64_tr_b16 v[124:125], v187 offset:0x2200
	ds_read_b64_tr_b16 v[126:127], v187 offset:0x2a00
	v_mfma_f32_32x32x16_bf16 v[0:15], v[112:115], v[128:131], v[0:15]
	ds_read_b64_tr_b16 v[128:129], v187 offset:0x3200
	ds_read_b64_tr_b16 v[130:131], v187 offset:0x3a00
	s_waitcnt lgkmcnt(0)
	v_mfma_f32_32x32x16_bf16 v[48:63], v[100:103], v[116:119], v[48:63]
	ds_read_b64_tr_b16 v[116:117], v187 offset:0x400
	ds_read_b64_tr_b16 v[118:119], v187 offset:0xc00
	v_mfma_f32_32x32x16_bf16 v[48:63], v[104:107], v[120:123], v[48:63]
	ds_read_b64_tr_b16 v[120:121], v187 offset:0x1400
	ds_read_b64_tr_b16 v[122:123], v187 offset:0x1c00
	v_mfma_f32_32x32x16_bf16 v[48:63], v[108:111], v[124:127], v[48:63]
	ds_read_b64_tr_b16 v[124:125], v187 offset:0x2400
	ds_read_b64_tr_b16 v[126:127], v187 offset:0x2c00
	v_mfma_f32_32x32x16_bf16 v[48:63], v[112:115], v[128:131], v[48:63]
	ds_read_b64_tr_b16 v[128:129], v187 offset:0x3400
	ds_read_b64_tr_b16 v[130:131], v187 offset:0x3c00
	s_waitcnt lgkmcnt(0)
	v_mfma_f32_32x32x16_bf16 v[32:47], v[100:103], v[116:119], v[32:47]
	ds_read_b64_tr_b16 v[116:117], v187 offset:0x600
	ds_read_b64_tr_b16 v[118:119], v187 offset:0xe00
	v_mfma_f32_32x32x16_bf16 v[32:47], v[104:107], v[120:123], v[32:47]
	ds_read_b64_tr_b16 v[120:121], v187 offset:0x1600
	ds_read_b64_tr_b16 v[122:123], v187 offset:0x1e00
	v_mfma_f32_32x32x16_bf16 v[32:47], v[108:111], v[124:127], v[32:47]
	ds_read_b64_tr_b16 v[124:125], v187 offset:0x2600
	ds_read_b64_tr_b16 v[126:127], v187 offset:0x2e00
	v_mfma_f32_32x32x16_bf16 v[32:47], v[112:115], v[128:131], v[32:47]
	ds_read_b64_tr_b16 v[128:129], v187 offset:0x3600
	ds_read_b64_tr_b16 v[130:131], v187 offset:0x3e00
	s_waitcnt lgkmcnt(0)
	v_mfma_f32_32x32x16_bf16 v[16:31], v[100:103], v[116:119], v[16:31]
	v_max_f32_e32 v100, v81, v81
	v_max_f32_e32 v101, v80, v80
	v_max_f32_e32 v100, v101, v100
	v_max3_f32 v100, v100, v82, v83
	v_max3_f32 v100, v100, v84, v85
	v_max3_f32 v100, v100, v86, v87
	v_max3_f32 v100, v100, v88, v89
	v_max3_f32 v100, v100, v90, v91
	v_max3_f32 v100, v100, v92, v93
	v_mfma_f32_32x32x16_bf16 v[16:31], v[104:107], v[120:123], v[16:31]
	v_max3_f32 v100, v100, v94, v95
	v_max3_f32 v100, v100, v64, v65
	v_max3_f32 v100, v100, v66, v67
	v_max3_f32 v100, v100, v68, v69
	v_max3_f32 v100, v100, v70, v71
	v_max3_f32 v100, v100, v72, v73
	v_max3_f32 v100, v100, v74, v75
	v_max3_f32 v100, v100, v76, v77
	v_mfma_f32_32x32x16_bf16 v[16:31], v[108:111], v[124:127], v[16:31]
	v_max3_f32 v100, v100, v78, v79
	v_mov_b32_e32 v101, v100
	s_nop 1
	v_permlane32_swap_b32_e32 v100, v101
	v_max_f32_e32 v101, v101, v101
	v_max_f32_e32 v100, v100, v100
	v_max_f32_e32 v100, v100, v101
	v_sub_f32_e32 v101, v100, v170
	v_cmp_ge_f32_e32 vcc, s92, v101
	v_max_f32_e32 v101, v170, v170
	v_max_f32_e32 v101, v101, v100
	v_mfma_f32_32x32x16_bf16 v[16:31], v[112:115], v[128:131], v[16:31]
	v_sub_f32_e32 v100, v170, v101
	v_mul_f32_e32 v100, 0x3e0293ee, v100
	v_exp_f32_e32 v100, v100
	s_cmp_eq_u64 vcc, exec
	s_cselect_b64 s[42:43], -1, 0
	v_cndmask_b32_e64 v100, v100, 1.0, s[42:43]
	v_cmp_gt_f32_e32 vcc, 1.0, v100
	s_barrier
	s_cbranch_vccz .LBB0_542
	s_and_saveexec_b64 s[6:7], s[40:41]
	ds_write_b32 v184, v100 offset:128
	s_or_b64 exec, exec, s[6:7]
	s_waitcnt lgkmcnt(0)
	ds_read_b128 v[102:105], v182 offset:224
	ds_read_b128 v[106:109], v182 offset:192
	ds_read_b128 v[110:113], v182 offset:160
	ds_read_b128 v[114:117], v182 offset:128
	s_waitcnt lgkmcnt(3)
	v_pk_mul_f32 v[14:15], v[14:15], v[104:105]
	s_waitcnt lgkmcnt(2)
	v_pk_mul_f32 v[10:11], v[10:11], v[108:109]
	s_waitcnt lgkmcnt(1)
	v_pk_mul_f32 v[6:7], v[6:7], v[112:113]
	s_waitcnt lgkmcnt(0)
	v_pk_mul_f32 v[2:3], v[2:3], v[116:117]
	v_pk_mul_f32 v[12:13], v[12:13], v[102:103]
	v_pk_mul_f32 v[8:9], v[8:9], v[106:107]
	v_pk_mul_f32 v[4:5], v[4:5], v[110:111]
	v_pk_mul_f32 v[0:1], v[0:1], v[114:115]
	v_pk_mul_f32 v[62:63], v[62:63], v[104:105]
	v_pk_mul_f32 v[58:59], v[58:59], v[108:109]
	v_pk_mul_f32 v[54:55], v[54:55], v[112:113]
	v_pk_mul_f32 v[50:51], v[50:51], v[116:117]
	v_pk_mul_f32 v[60:61], v[60:61], v[102:103]
	v_pk_mul_f32 v[56:57], v[56:57], v[106:107]
	v_pk_mul_f32 v[52:53], v[52:53], v[110:111]
	v_pk_mul_f32 v[48:49], v[48:49], v[114:115]
	v_pk_mul_f32 v[46:47], v[46:47], v[104:105]
	v_pk_mul_f32 v[42:43], v[42:43], v[108:109]
	v_pk_mul_f32 v[38:39], v[38:39], v[112:113]
	v_pk_mul_f32 v[34:35], v[34:35], v[116:117]
	v_pk_mul_f32 v[44:45], v[44:45], v[102:103]
	v_pk_mul_f32 v[40:41], v[40:41], v[106:107]
	v_pk_mul_f32 v[36:37], v[36:37], v[110:111]
	v_pk_mul_f32 v[32:33], v[32:33], v[114:115]
	v_pk_mul_f32 v[30:31], v[30:31], v[104:105]
	v_pk_mul_f32 v[26:27], v[26:27], v[108:109]
	v_pk_mul_f32 v[22:23], v[22:23], v[112:113]
	v_pk_mul_f32 v[18:19], v[18:19], v[116:117]
	v_pk_mul_f32 v[28:29], v[28:29], v[102:103]
	v_pk_mul_f32 v[24:25], v[24:25], v[106:107]
	v_pk_mul_f32 v[20:21], v[20:21], v[110:111]
	v_pk_mul_f32 v[16:17], v[16:17], v[114:115]
